# stack: deferred queue-atomic wait + snake MFMA order (bf16 K-loops) + priority flip every 8 MFMAs + P6 gain preload + P4 grouped x loads
# speedup vs baseline: 1.0074x; 1.0074x over previous
; #define PG8_LDA(dst, b, h) do { if constexpr (FP8) { _Pragma("unroll") for (int m = 0; m < 4; ++m) dst##8[m] = PG8_LD8(PG8_SA(b, h), aoff, aoff1, m); } \
;         else { _Pragma("unroll") for (int m = 0; m < 4; ++m) _Pragma("unroll") for (int k = 0; k < 2; ++k) dst[m][k] = *(const LAS bf16x8*)(lds + PG8_SA(b, h) + (k ? aoff1 : aoff) + m * 2048); } } while (0)
; #define PG8_LDB(dst, b, h) do { if constexpr (FP8) { dst##8[0] = PG8_LD8(PG8_SB(b, h), boff, boff1, 0); dst##8[1] = PG8_LD8(PG8_SB(b, h), boff, boff1, 1); } \
;         else { _Pragma("unroll") for (int n = 0; n < 2; ++n) _Pragma("unroll") for (int k = 0; k < 2; ++k) dst[n][k] = *(const LAS bf16x8*)(lds + PG8_SB(b, h) + (k ? boff1 : boff) + n * 2048); } } while (0)
; #define PG8_WAIT_V(n) asm volatile("s_waitcnt vmcnt(" #n ")" ::: "memory")
; #define PG8_WAIT_L(n) asm volatile("s_waitcnt lgkmcnt(" #n ")" ::: "memory")
; #define PG8_BAR __builtin_amdgcn_s_barrier()
; #define PG8_SCHED __builtin_amdgcn_sched_barrier(0)
; #define PG8_S1 PG8_STAGE(PG8_SA(1, 1), a1 + hstepA, voffA)
; #define PG8_S2 do { PG8_STAGE(PG8_SB(0, 0), b2, voffB); PG8_STAGE(PG8_SB(0, 1), b2 + hstepB, voffB); PG8_STAGE(PG8_SA(0, 0), a2, voffA); } while (0)
; template <class Epi, class SchedT, bool ALIGN_EPI, bool SP2, bool FP8 = false>
; __device__ __forceinline__ void gemm_phase(LAS unsigned char* lds, const Gemm g, const SchedT& S, const Epi& E, const int wid) {
;     ...
;             const bool last = (t == nt - 2);
;             const char* a1 = cA + (size_t)(t + 1) * kstep;
;             const char* a2 = last ? nA : cA + (size_t)(t + 2) * kstep; const char* b2 = last ? nB : cB + (size_t)(t + 2) * kstep;
;             const char* a3 = a2 + kstep; const char* b3 = b2 + kstep;
;     ...
;             PG8_LDB(B0, 0, 0); PG8_LDB(B1, 0, 1); PG8_SCHED; PG8_LDA(At, 0, 0); PG8_S1;
;             PG8_WAIT_V(8); PG8_WAIT_L(0); PG8_BAR; PG8_MMAP(0, 0, 0); PG8_BAR; PG8_SCHED;
;             PG8_LDA(At, 0, 1); PG8_S2;
;             PG8_WAIT_V(8); PG8_WAIT_L(0); PG8_BAR; PG8_MMAP(1, 0, 1); PG8_BAR; PG8_SCHED;
.LBB0_256:
	ds_read_b128 v[146:149], v139
	ds_read_b128 v[150:153], v139 offset:1024
	ds_read_b128 v[154:157], v140
	ds_read_b128 v[158:161], v140 offset:1024
	ds_read_b128 v[162:165], v141
	ds_read_b128 v[166:169], v141 offset:1024
	ds_read_b128 v[170:173], v142
	ds_read_b128 v[174:177], v142 offset:1024
	s_add_i32 s43, s39, 2
	s_add_u32 s6, s50, 0xfffc0080
	s_addc_u32 s7, s51, -1
	s_cmp_eq_u32 s30, s39
	s_cselect_b32 s53, s9, s7
	s_cselect_b32 s52, s20, s6
	s_cselect_b32 s67, s21, s38
	s_cselect_b32 s66, s24, s31
	v_mov_b32_e32 v128, v134
	ds_read_b128 v[178:181], v143
	ds_read_b128 v[182:185], v143 offset:1024
	ds_read_b128 v[186:189], v143 offset:2048
	ds_read_b128 v[190:193], v143 offset:3072
	ds_read_b128 v[194:197], v143 offset:4096
	ds_read_b128 v[198:201], v143 offset:5120
	ds_read_b128 v[202:205], v143 offset:6144
	ds_read_b128 v[206:209], v143 offset:7168
	s_add_i32 m0, s87, 0xc000
	s_nop 0
	global_load_lds_dwordx4 v128, s[50:51]
	v_mov_b32_e32 v128, v136
	s_add_i32 m0, s87, 0xe000
	s_nop 0
	global_load_lds_dwordx4 v128, s[50:51]
	s_waitcnt vmcnt(8)
	s_waitcnt lgkmcnt(0)
	s_barrier
	s_setprio 1
	s_waitcnt lgkmcnt(0)
	v_mfma_f32_16x16x32_bf16 v[124:127], v[146:149], v[178:181], v[124:127]
	v_mfma_f32_16x16x32_bf16 v[120:123], v[154:157], v[178:181], v[120:123]
	v_mfma_f32_16x16x32_bf16 v[104:107], v[154:157], v[186:189], v[104:107]
	v_mfma_f32_16x16x32_bf16 v[108:111], v[146:149], v[186:189], v[108:111]
	v_mfma_f32_16x16x32_bf16 v[92:95], v[146:149], v[194:197], v[92:95]
	v_mfma_f32_16x16x32_bf16 v[88:91], v[154:157], v[194:197], v[88:91]
	v_mfma_f32_16x16x32_bf16 v[72:75], v[154:157], v[202:205], v[72:75]
	v_mfma_f32_16x16x32_bf16 v[76:79], v[146:149], v[202:205], v[76:79]
	v_mfma_f32_16x16x32_bf16 v[124:127], v[150:153], v[182:185], v[124:127]
	v_mfma_f32_16x16x32_bf16 v[120:123], v[158:161], v[182:185], v[120:123]
	v_mfma_f32_16x16x32_bf16 v[104:107], v[158:161], v[190:193], v[104:107]
	v_mfma_f32_16x16x32_bf16 v[108:111], v[150:153], v[190:193], v[108:111]
	v_mfma_f32_16x16x32_bf16 v[92:95], v[150:153], v[198:201], v[92:95]
	v_mfma_f32_16x16x32_bf16 v[88:91], v[158:161], v[198:201], v[88:91]
	v_mfma_f32_16x16x32_bf16 v[72:75], v[158:161], v[206:209], v[72:75]
	v_mfma_f32_16x16x32_bf16 v[76:79], v[150:153], v[206:209], v[76:79]
	s_setprio 0
	s_setprio 1
	v_mfma_f32_16x16x32_bf16 v[116:119], v[162:165], v[178:181], v[116:119]
	v_mfma_f32_16x16x32_bf16 v[112:115], v[170:173], v[178:181], v[112:115]
	v_mfma_f32_16x16x32_bf16 v[96:99], v[170:173], v[186:189], v[96:99]
	v_mfma_f32_16x16x32_bf16 v[100:103], v[162:165], v[186:189], v[100:103]
	v_mfma_f32_16x16x32_bf16 v[84:87], v[162:165], v[194:197], v[84:87]
	v_mfma_f32_16x16x32_bf16 v[80:83], v[170:173], v[194:197], v[80:83]
	v_mfma_f32_16x16x32_bf16 v[56:59], v[170:173], v[202:205], v[56:59]
	v_mfma_f32_16x16x32_bf16 v[60:63], v[162:165], v[202:205], v[60:63]
	v_mfma_f32_16x16x32_bf16 v[116:119], v[166:169], v[182:185], v[116:119]
	v_mfma_f32_16x16x32_bf16 v[112:115], v[174:177], v[182:185], v[112:115]
	v_mfma_f32_16x16x32_bf16 v[96:99], v[174:177], v[190:193], v[96:99]
	v_mfma_f32_16x16x32_bf16 v[100:103], v[166:169], v[190:193], v[100:103]
	v_mfma_f32_16x16x32_bf16 v[84:87], v[166:169], v[198:201], v[84:87]
	v_mfma_f32_16x16x32_bf16 v[80:83], v[174:177], v[198:201], v[80:83]
	v_mfma_f32_16x16x32_bf16 v[56:59], v[174:177], v[206:209], v[56:59]
	v_mfma_f32_16x16x32_bf16 v[60:63], v[166:169], v[206:209], v[60:63]
	s_setprio 0
	s_barrier
	v_mov_b32_e32 v128, v135
	s_add_i32 s6, s94, s86
	ds_read_b128 v[178:181], v143 offset:16384
	ds_read_b128 v[182:185], v143 offset:17408
	ds_read_b128 v[186:189], v143 offset:18432
	ds_read_b128 v[190:193], v143 offset:19456
	ds_read_b128 v[194:197], v143 offset:20480
	ds_read_b128 v[198:201], v143 offset:21504
	ds_read_b128 v[202:205], v143 offset:22528
	ds_read_b128 v[206:209], v143 offset:23552
	s_mov_b32 m0, s6
	s_nop 0
	global_load_lds_dwordx4 v128, s[66:67]
	v_mov_b32_e32 v128, v137
	s_add_i32 m0, s6, 0x2000
	s_add_u32 s60, s66, 0x40000
	global_load_lds_dwordx4 v128, s[66:67]
	s_addc_u32 s61, s67, 0
	v_mov_b32_e32 v128, v135
	s_add_i32 s6, s95, s86
	s_mov_b32 m0, s6
	s_nop 0
	global_load_lds_dwordx4 v128, s[60:61]
	v_mov_b32_e32 v128, v137
	s_add_i32 m0, s6, 0x2000
	s_nop 0
	global_load_lds_dwordx4 v128, s[60:61]
	v_mov_b32_e32 v128, v134
	s_mov_b32 m0, s87
	s_nop 0
	global_load_lds_dwordx4 v128, s[52:53]
	v_mov_b32_e32 v128, v136
	s_mov_b32 m0, s88
	s_nop 0
	global_load_lds_dwordx4 v128, s[52:53]
	s_waitcnt vmcnt(8)
	s_waitcnt lgkmcnt(0)
	s_barrier
; #define PG8_LDA(dst, b, h) do { if constexpr (FP8) { _Pragma("unroll") for (int m = 0; m < 4; ++m) dst##8[m] = PG8_LD8(PG8_SA(b, h), aoff, aoff1, m); } \
;         else { _Pragma("unroll") for (int m = 0; m < 4; ++m) _Pragma("unroll") for (int k = 0; k < 2; ++k) dst[m][k] = *(const LAS bf16x8*)(lds + PG8_SA(b, h) + (k ? aoff1 : aoff) + m * 2048); } } while (0)
; #define PG8_LDB(dst, b, h) do { if constexpr (FP8) { dst##8[0] = PG8_LD8(PG8_SB(b, h), boff, boff1, 0); dst##8[1] = PG8_LD8(PG8_SB(b, h), boff, boff1, 1); } \
;         else { _Pragma("unroll") for (int n = 0; n < 2; ++n) _Pragma("unroll") for (int k = 0; k < 2; ++k) dst[n][k] = *(const LAS bf16x8*)(lds + PG8_SB(b, h) + (k ? boff1 : boff) + n * 2048); } } while (0)
; #define PG8_WAIT_V(n) asm volatile("s_waitcnt vmcnt(" #n ")" ::: "memory")
; #define PG8_WAIT_L(n) asm volatile("s_waitcnt lgkmcnt(" #n ")" ::: "memory")
; #define PG8_BAR __builtin_amdgcn_s_barrier()
; #define PG8_SCHED __builtin_amdgcn_sched_barrier(0)
; #define PG8_S3 PG8_STAGE(PG8_SA(0, 1), a2 + hstepA, voffA)
; template <class Epi, class SchedT, bool ALIGN_EPI, bool SP2, bool FP8 = false>
; __device__ __forceinline__ void gemm_phase(LAS unsigned char* lds, const Gemm g, const SchedT& S, const Epi& E, const int wid) {
;     ...
;             PG8_WAIT_V(8); PG8_WAIT_L(0); PG8_BAR; PG8_MMAP(1, 0, 1); PG8_BAR; PG8_SCHED;
;             PG8_LDB(B0, 1, 0); PG8_LDB(B1, 1, 1); PG8_SCHED; PG8_LDA(At, 1, 0); PG8_S3;
;             PG8_WAIT_V(8); PG8_WAIT_L(0); PG8_BAR; PG8_MMAP(0, 1, 0); PG8_BAR; PG8_SCHED;
	s_setprio 1
	s_waitcnt lgkmcnt(0)
	v_mfma_f32_16x16x32_bf16 v[68:71], v[146:149], v[178:181], v[68:71]
	v_mfma_f32_16x16x32_bf16 v[64:67], v[154:157], v[178:181], v[64:67]
	v_mfma_f32_16x16x32_bf16 v[40:43], v[154:157], v[186:189], v[40:43]
	v_mfma_f32_16x16x32_bf16 v[44:47], v[146:149], v[186:189], v[44:47]
	v_mfma_f32_16x16x32_bf16 v[28:31], v[146:149], v[194:197], v[28:31]
	v_mfma_f32_16x16x32_bf16 v[24:27], v[154:157], v[194:197], v[24:27]
	v_mfma_f32_16x16x32_bf16 v[8:11], v[154:157], v[202:205], v[8:11]
	v_mfma_f32_16x16x32_bf16 v[12:15], v[146:149], v[202:205], v[12:15]
	v_mfma_f32_16x16x32_bf16 v[68:71], v[150:153], v[182:185], v[68:71]
	v_mfma_f32_16x16x32_bf16 v[64:67], v[158:161], v[182:185], v[64:67]
	v_mfma_f32_16x16x32_bf16 v[40:43], v[158:161], v[190:193], v[40:43]
	v_mfma_f32_16x16x32_bf16 v[44:47], v[150:153], v[190:193], v[44:47]
	v_mfma_f32_16x16x32_bf16 v[28:31], v[150:153], v[198:201], v[28:31]
	v_mfma_f32_16x16x32_bf16 v[24:27], v[158:161], v[198:201], v[24:27]
	v_mfma_f32_16x16x32_bf16 v[8:11], v[158:161], v[206:209], v[8:11]
	v_mfma_f32_16x16x32_bf16 v[12:15], v[150:153], v[206:209], v[12:15]
	s_setprio 0
	s_setprio 1
	v_mfma_f32_16x16x32_bf16 v[52:55], v[162:165], v[178:181], v[52:55]
	v_mfma_f32_16x16x32_bf16 v[48:51], v[170:173], v[178:181], v[48:51]
	v_mfma_f32_16x16x32_bf16 v[32:35], v[170:173], v[186:189], v[32:35]
	v_mfma_f32_16x16x32_bf16 v[36:39], v[162:165], v[186:189], v[36:39]
	v_mfma_f32_16x16x32_bf16 v[20:23], v[162:165], v[194:197], v[20:23]
	v_mfma_f32_16x16x32_bf16 v[16:19], v[170:173], v[194:197], v[16:19]
	v_mfma_f32_16x16x32_bf16 v[0:3], v[170:173], v[202:205], v[0:3]
	v_mfma_f32_16x16x32_bf16 v[4:7], v[162:165], v[202:205], v[4:7]
	v_mfma_f32_16x16x32_bf16 v[52:55], v[166:169], v[182:185], v[52:55]
	v_mfma_f32_16x16x32_bf16 v[48:51], v[174:177], v[182:185], v[48:51]
	v_mfma_f32_16x16x32_bf16 v[32:35], v[174:177], v[190:193], v[32:35]
	v_mfma_f32_16x16x32_bf16 v[36:39], v[166:169], v[190:193], v[36:39]
	v_mfma_f32_16x16x32_bf16 v[20:23], v[166:169], v[198:201], v[20:23]
	v_mfma_f32_16x16x32_bf16 v[16:19], v[174:177], v[198:201], v[16:19]
	v_mfma_f32_16x16x32_bf16 v[0:3], v[174:177], v[206:209], v[0:3]
	v_mfma_f32_16x16x32_bf16 v[4:7], v[166:169], v[206:209], v[4:7]
	s_setprio 0
	s_barrier
	s_add_i32 s6, 0, 0x18000
	v_add_u32_e32 v128, s6, v138
	s_add_i32 s7, 0, 0x1c000
	ds_read_b128 v[146:149], v128
	ds_read_b128 v[150:153], v128 offset:1024
	ds_read_b128 v[154:157], v144
	ds_read_b128 v[158:161], v144 offset:1024
	v_add_u32_e32 v128, s7, v138
	ds_read_b128 v[162:165], v128
	ds_read_b128 v[166:169], v128 offset:1024
	ds_read_b128 v[170:173], v145
	ds_read_b128 v[174:177], v145 offset:1024
	s_add_u32 s60, s52, 0x40000
	v_mov_b32_e32 v128, v134
	s_mov_b32 m0, s89
	ds_read_b128 v[178:181], v143 offset:32768
	ds_read_b128 v[182:185], v143 offset:33792
	ds_read_b128 v[186:189], v143 offset:34816
	ds_read_b128 v[190:193], v143 offset:35840
	ds_read_b128 v[194:197], v143 offset:36864
	ds_read_b128 v[198:201], v143 offset:37888
	ds_read_b128 v[202:205], v143 offset:38912
	ds_read_b128 v[206:209], v143 offset:39936
	s_addc_u32 s61, s53, 0
	s_nop 0
	global_load_lds_dwordx4 v128, s[60:61]
	v_mov_b32_e32 v128, v136
	s_mov_b32 m0, s90
	s_nop 0
	global_load_lds_dwordx4 v128, s[60:61]
	s_waitcnt vmcnt(8)
	s_waitcnt lgkmcnt(0)
	s_barrier
	s_setprio 1
	s_waitcnt lgkmcnt(0)
	v_mfma_f32_16x16x32_bf16 v[124:127], v[146:149], v[178:181], v[124:127]
	v_mfma_f32_16x16x32_bf16 v[120:123], v[154:157], v[178:181], v[120:123]
	v_mfma_f32_16x16x32_bf16 v[104:107], v[154:157], v[186:189], v[104:107]
	v_mfma_f32_16x16x32_bf16 v[108:111], v[146:149], v[186:189], v[108:111]
	v_mfma_f32_16x16x32_bf16 v[92:95], v[146:149], v[194:197], v[92:95]
	v_mfma_f32_16x16x32_bf16 v[88:91], v[154:157], v[194:197], v[88:91]
	v_mfma_f32_16x16x32_bf16 v[72:75], v[154:157], v[202:205], v[72:75]
	v_mfma_f32_16x16x32_bf16 v[76:79], v[146:149], v[202:205], v[76:79]
	v_mfma_f32_16x16x32_bf16 v[124:127], v[150:153], v[182:185], v[124:127]
	v_mfma_f32_16x16x32_bf16 v[120:123], v[158:161], v[182:185], v[120:123]
	v_mfma_f32_16x16x32_bf16 v[104:107], v[158:161], v[190:193], v[104:107]
	v_mfma_f32_16x16x32_bf16 v[108:111], v[150:153], v[190:193], v[108:111]
	v_mfma_f32_16x16x32_bf16 v[92:95], v[150:153], v[198:201], v[92:95]
	v_mfma_f32_16x16x32_bf16 v[88:91], v[158:161], v[198:201], v[88:91]
	v_mfma_f32_16x16x32_bf16 v[72:75], v[158:161], v[206:209], v[72:75]
	v_mfma_f32_16x16x32_bf16 v[76:79], v[150:153], v[206:209], v[76:79]
	s_setprio 0
	s_setprio 1
	v_mfma_f32_16x16x32_bf16 v[116:119], v[162:165], v[178:181], v[116:119]
	v_mfma_f32_16x16x32_bf16 v[112:115], v[170:173], v[178:181], v[112:115]
	v_mfma_f32_16x16x32_bf16 v[96:99], v[170:173], v[186:189], v[96:99]
	v_mfma_f32_16x16x32_bf16 v[100:103], v[162:165], v[186:189], v[100:103]
	v_mfma_f32_16x16x32_bf16 v[84:87], v[162:165], v[194:197], v[84:87]
	v_mfma_f32_16x16x32_bf16 v[80:83], v[170:173], v[194:197], v[80:83]
	v_mfma_f32_16x16x32_bf16 v[56:59], v[170:173], v[202:205], v[56:59]
	v_mfma_f32_16x16x32_bf16 v[60:63], v[162:165], v[202:205], v[60:63]
	v_mfma_f32_16x16x32_bf16 v[116:119], v[166:169], v[182:185], v[116:119]
	v_mfma_f32_16x16x32_bf16 v[112:115], v[174:177], v[182:185], v[112:115]
	v_mfma_f32_16x16x32_bf16 v[96:99], v[174:177], v[190:193], v[96:99]
	v_mfma_f32_16x16x32_bf16 v[100:103], v[166:169], v[190:193], v[100:103]
	v_mfma_f32_16x16x32_bf16 v[84:87], v[166:169], v[198:201], v[84:87]
	v_mfma_f32_16x16x32_bf16 v[80:83], v[174:177], v[198:201], v[80:83]
	v_mfma_f32_16x16x32_bf16 v[56:59], v[174:177], v[206:209], v[56:59]
	v_mfma_f32_16x16x32_bf16 v[60:63], v[166:169], v[206:209], v[60:63]
	s_setprio 0
	s_barrier
; #define PG8_LDA(dst, b, h) do { if constexpr (FP8) { _Pragma("unroll") for (int m = 0; m < 4; ++m) dst##8[m] = PG8_LD8(PG8_SA(b, h), aoff, aoff1, m); } \
;         else { _Pragma("unroll") for (int m = 0; m < 4; ++m) _Pragma("unroll") for (int k = 0; k < 2; ++k) dst[m][k] = *(const LAS bf16x8*)(lds + PG8_SA(b, h) + (k ? aoff1 : aoff) + m * 2048); } } while (0)
; #define PG8_LDB(dst, b, h) do { if constexpr (FP8) { dst##8[0] = PG8_LD8(PG8_SB(b, h), boff, boff1, 0); dst##8[1] = PG8_LD8(PG8_SB(b, h), boff, boff1, 1); } \
;         else { _Pragma("unroll") for (int n = 0; n < 2; ++n) _Pragma("unroll") for (int k = 0; k < 2; ++k) dst[n][k] = *(const LAS bf16x8*)(lds + PG8_SB(b, h) + (k ? boff1 : boff) + n * 2048); } } while (0)
; #define PG8_WAIT_V(n) asm volatile("s_waitcnt vmcnt(" #n ")" ::: "memory")
; #define PG8_WAIT_L(n) asm volatile("s_waitcnt lgkmcnt(" #n ")" ::: "memory")
; #define PG8_BAR __builtin_amdgcn_s_barrier()
; #define PG8_SCHED __builtin_amdgcn_sched_barrier(0)
; #define PG8_S1 PG8_STAGE(PG8_SA(1, 1), a1 + hstepA, voffA)
; #define PG8_S3 PG8_STAGE(PG8_SA(0, 1), a2 + hstepA, voffA)
; template <class Epi, class SchedT, bool ALIGN_EPI, bool SP2, bool FP8 = false>
; __device__ __forceinline__ void gemm_phase(LAS unsigned char* lds, const Gemm g, const SchedT& S, const Epi& E, const int wid) {
;     ...
;         for (int t = 0; t < nt; t += 2) {
;             const bool last = (t == nt - 2);
;             const char* a1 = cA + (size_t)(t + 1) * kstep;
;             const char* a2 = last ? nA : cA + (size_t)(t + 2) * kstep; const char* b2 = last ? nB : cB + (size_t)(t + 2) * kstep;
;             const char* a3 = a2 + kstep; const char* b3 = b2 + kstep;
;     ...
;             PG8_LDB(B0, 0, 0); PG8_LDB(B1, 0, 1); PG8_SCHED; PG8_LDA(At, 0, 0); PG8_S1;
;             PG8_WAIT_V(8); PG8_WAIT_L(0); PG8_BAR; PG8_MMAP(0, 0, 0); PG8_BAR; PG8_SCHED;
;             PG8_LDA(At, 0, 1); PG8_S2;
;             PG8_WAIT_V(8); PG8_WAIT_L(0); PG8_BAR; PG8_MMAP(1, 0, 1); PG8_BAR; PG8_SCHED;
;             PG8_LDB(B0, 1, 0); PG8_LDB(B1, 1, 1); PG8_SCHED; PG8_LDA(At, 1, 0); PG8_S3;
;             PG8_WAIT_V(8); PG8_WAIT_L(0); PG8_BAR; PG8_MMAP(0, 1, 0); PG8_BAR; PG8_SCHED;
;             PG8_LDA(At, 1, 1); PG8_S4;
;             PG8_WAIT_V(8); PG8_WAIT_L(0); PG8_BAR; PG8_MMAP(1, 1, 1); PG8_BAR; PG8_SCHED;
	v_mov_b32_e32 v128, v135
	ds_read_b128 v[178:181], v143 offset:49152
	ds_read_b128 v[182:185], v143 offset:50176
	ds_read_b128 v[186:189], v143 offset:51200
	ds_read_b128 v[190:193], v143 offset:52224
	ds_read_b128 v[194:197], v143 offset:53248
	ds_read_b128 v[198:201], v143 offset:54272
	ds_read_b128 v[202:205], v143 offset:55296
	ds_read_b128 v[206:209], v143 offset:56320
	s_add_i32 s6, s6, s86
	v_lshl_add_u64 v[210:211], s[66:67], 0, v[128:129]
	v_lshl_add_u64 v[210:211], v[210:211], 0, s[36:37]
	s_mov_b32 m0, s6
	v_mov_b32_e32 v128, v137
	global_load_lds_dwordx4 v[210:211], off
	s_add_i32 m0, s6, 0x2000
	s_add_u32 s60, s66, 0x40080
	v_lshl_add_u64 v[210:211], s[66:67], 0, v[128:129]
	v_lshl_add_u64 v[210:211], v[210:211], 0, s[36:37]
	s_addc_u32 s61, s67, 0
	v_mov_b32_e32 v128, v135
	s_add_i32 s6, s7, s86
	global_load_lds_dwordx4 v[210:211], off
	s_mov_b32 m0, s6
	s_nop 0
	global_load_lds_dwordx4 v128, s[60:61]
	v_mov_b32_e32 v128, v137
	s_add_i32 m0, s6, 0x2000
	s_nop 0
	global_load_lds_dwordx4 v128, s[60:61]
	v_mov_b32_e32 v128, v134
	s_mov_b32 m0, s92
	v_lshl_add_u64 v[210:211], s[52:53], 0, v[128:129]
	v_lshl_add_u64 v[210:211], v[210:211], 0, s[36:37]
	v_mov_b32_e32 v128, v136
	global_load_lds_dwordx4 v[210:211], off
	s_mov_b32 m0, s93
	v_lshl_add_u64 v[210:211], s[52:53], 0, v[128:129]
	v_lshl_add_u64 v[210:211], v[210:211], 0, s[36:37]
	global_load_lds_dwordx4 v[210:211], off
	s_waitcnt vmcnt(8)
	s_waitcnt lgkmcnt(0)
	s_barrier
	s_setprio 1
	s_waitcnt lgkmcnt(0)
	v_mfma_f32_16x16x32_bf16 v[68:71], v[146:149], v[178:181], v[68:71]
	v_mfma_f32_16x16x32_bf16 v[64:67], v[154:157], v[178:181], v[64:67]
	v_mfma_f32_16x16x32_bf16 v[40:43], v[154:157], v[186:189], v[40:43]
	v_mfma_f32_16x16x32_bf16 v[44:47], v[146:149], v[186:189], v[44:47]
	v_mfma_f32_16x16x32_bf16 v[28:31], v[146:149], v[194:197], v[28:31]
	v_mfma_f32_16x16x32_bf16 v[24:27], v[154:157], v[194:197], v[24:27]
	v_mfma_f32_16x16x32_bf16 v[8:11], v[154:157], v[202:205], v[8:11]
	v_mfma_f32_16x16x32_bf16 v[12:15], v[146:149], v[202:205], v[12:15]
	v_mfma_f32_16x16x32_bf16 v[68:71], v[150:153], v[182:185], v[68:71]
	v_mfma_f32_16x16x32_bf16 v[64:67], v[158:161], v[182:185], v[64:67]
	v_mfma_f32_16x16x32_bf16 v[40:43], v[158:161], v[190:193], v[40:43]
	v_mfma_f32_16x16x32_bf16 v[44:47], v[150:153], v[190:193], v[44:47]
	v_mfma_f32_16x16x32_bf16 v[28:31], v[150:153], v[198:201], v[28:31]
	v_mfma_f32_16x16x32_bf16 v[24:27], v[158:161], v[198:201], v[24:27]
	v_mfma_f32_16x16x32_bf16 v[8:11], v[158:161], v[206:209], v[8:11]
	v_mfma_f32_16x16x32_bf16 v[12:15], v[150:153], v[206:209], v[12:15]
	s_setprio 0
	s_setprio 1
	v_mfma_f32_16x16x32_bf16 v[52:55], v[162:165], v[178:181], v[52:55]
	v_mfma_f32_16x16x32_bf16 v[48:51], v[170:173], v[178:181], v[48:51]
	v_mfma_f32_16x16x32_bf16 v[32:35], v[170:173], v[186:189], v[32:35]
	v_mfma_f32_16x16x32_bf16 v[36:39], v[162:165], v[186:189], v[36:39]
	v_mfma_f32_16x16x32_bf16 v[20:23], v[162:165], v[194:197], v[20:23]
	v_mfma_f32_16x16x32_bf16 v[16:19], v[170:173], v[194:197], v[16:19]
	v_mfma_f32_16x16x32_bf16 v[0:3], v[170:173], v[202:205], v[0:3]
	v_mfma_f32_16x16x32_bf16 v[4:7], v[162:165], v[202:205], v[4:7]
	v_mfma_f32_16x16x32_bf16 v[52:55], v[166:169], v[182:185], v[52:55]
	v_mfma_f32_16x16x32_bf16 v[48:51], v[174:177], v[182:185], v[48:51]
	v_mfma_f32_16x16x32_bf16 v[32:35], v[174:177], v[190:193], v[32:35]
	v_mfma_f32_16x16x32_bf16 v[36:39], v[166:169], v[190:193], v[36:39]
	v_mfma_f32_16x16x32_bf16 v[20:23], v[166:169], v[198:201], v[20:23]
	v_mfma_f32_16x16x32_bf16 v[16:19], v[174:177], v[198:201], v[16:19]
	v_mfma_f32_16x16x32_bf16 v[0:3], v[174:177], v[206:209], v[0:3]
	v_mfma_f32_16x16x32_bf16 v[4:7], v[166:169], v[206:209], v[4:7]
	s_setprio 0
	s_barrier
	s_add_u32 s50, s50, 0x100
	s_addc_u32 s51, s51, 0
	s_add_u32 s31, s31, 0x100
	s_addc_u32 s38, s38, 0
	s_cmp_ge_i32 s43, s8
	s_mov_b32 s39, s43
	s_cbranch_scc0 .LBB0_256
	s_and_b64 vcc, exec, s[96:97]
	s_cbranch_vccz .LBB0_259

; #define PG8_LDA(dst, b, h) do { if constexpr (FP8) { _Pragma("unroll") for (int m = 0; m < 4; ++m) dst##8[m] = PG8_LD8(PG8_SA(b, h), aoff, aoff1, m); } \
;         else { _Pragma("unroll") for (int m = 0; m < 4; ++m) _Pragma("unroll") for (int k = 0; k < 2; ++k) dst[m][k] = *(const LAS bf16x8*)(lds + PG8_SA(b, h) + (k ? aoff1 : aoff) + m * 2048); } } while (0)
; #define PG8_LDB(dst, b, h) do { if constexpr (FP8) { dst##8[0] = PG8_LD8(PG8_SB(b, h), boff, boff1, 0); dst##8[1] = PG8_LD8(PG8_SB(b, h), boff, boff1, 1); } \
;         else { _Pragma("unroll") for (int n = 0; n < 2; ++n) _Pragma("unroll") for (int k = 0; k < 2; ++k) dst[n][k] = *(const LAS bf16x8*)(lds + PG8_SB(b, h) + (k ? boff1 : boff) + n * 2048); } } while (0)
; #define PG8_WAIT_V(n) asm volatile("s_waitcnt vmcnt(" #n ")" ::: "memory")
; #define PG8_WAIT_L(n) asm volatile("s_waitcnt lgkmcnt(" #n ")" ::: "memory")
; #define PG8_BAR __builtin_amdgcn_s_barrier()
; #define PG8_SCHED __builtin_amdgcn_sched_barrier(0)
; #define PG8_S1 PG8_STAGE(PG8_SA(1, 1), a1 + hstepA, voffA)
; #define PG8_S2 do { PG8_STAGE(PG8_SB(0, 0), b2, voffB); PG8_STAGE(PG8_SB(0, 1), b2 + hstepB, voffB); PG8_STAGE(PG8_SA(0, 0), a2, voffA); } while (0)
; template <class Epi, class SchedT, bool ALIGN_EPI, bool SP2, bool FP8 = false>
; __device__ __forceinline__ void gemm_phase(LAS unsigned char* lds, const Gemm g, const SchedT& S, const Epi& E, const int wid) {
;     ...
;             const bool last = (t == nt - 2);
;             const char* a1 = cA + (size_t)(t + 1) * kstep;
;             const char* a2 = last ? nA : cA + (size_t)(t + 2) * kstep; const char* b2 = last ? nB : cB + (size_t)(t + 2) * kstep;
;             const char* a3 = a2 + kstep; const char* b3 = b2 + kstep;
;     ...
;             PG8_LDB(B0, 0, 0); PG8_LDB(B1, 0, 1); PG8_SCHED; PG8_LDA(At, 0, 0); PG8_S1;
;             PG8_WAIT_V(8); PG8_WAIT_L(0); PG8_BAR; PG8_MMAP(0, 0, 0); PG8_BAR; PG8_SCHED;
;             PG8_LDA(At, 0, 1); PG8_S2;
;             PG8_WAIT_V(8); PG8_WAIT_L(0); PG8_BAR; PG8_MMAP(1, 0, 1); PG8_BAR; PG8_SCHED;
.LBB0_899:
	ds_read_b128 v[128:131], v173
	ds_read_b128 v[132:135], v173 offset:1024
	ds_read_b128 v[136:139], v174
	ds_read_b128 v[140:143], v174 offset:1024
	ds_read_b128 v[150:153], v175
	ds_read_b128 v[154:157], v175 offset:1024
	ds_read_b128 v[158:161], v176
	ds_read_b128 v[162:165], v176 offset:1024
	s_add_i32 s35, s34, 2
	s_add_u32 s16, s48, 0xfffc0080
	s_addc_u32 s17, s49, -1
	s_cmp_eq_u32 s27, s34
	s_cselect_b32 s51, s15, s17
	s_cselect_b32 s50, s21, s16
	s_cselect_b32 s53, s24, s31
	s_cselect_b32 s52, s25, s30
	v_mov_b32_e32 v144, v168
	ds_read_b128 v[182:185], v177
	ds_read_b128 v[186:189], v177 offset:1024
	ds_read_b128 v[190:193], v177 offset:2048
	ds_read_b128 v[194:197], v177 offset:3072
	ds_read_b128 v[198:201], v177 offset:4096
	ds_read_b128 v[202:205], v177 offset:5120
	ds_read_b128 v[206:209], v177 offset:6144
	ds_read_b128 v[210:213], v177 offset:7168
	s_add_i32 m0, s87, 0xc000
	s_nop 0
	global_load_lds_dwordx4 v144, s[48:49]
	v_mov_b32_e32 v144, v170
	s_add_i32 m0, s87, 0xe000
	s_nop 0
	global_load_lds_dwordx4 v144, s[48:49]
	s_waitcnt vmcnt(8)
	s_waitcnt lgkmcnt(0)
	s_barrier
	s_setprio 1
	s_waitcnt lgkmcnt(0)
	v_mfma_f32_16x16x32_bf16 v[124:127], v[128:131], v[182:185], v[124:127]
	v_mfma_f32_16x16x32_bf16 v[120:123], v[136:139], v[182:185], v[120:123]
	v_mfma_f32_16x16x32_bf16 v[104:107], v[136:139], v[190:193], v[104:107]
	v_mfma_f32_16x16x32_bf16 v[108:111], v[128:131], v[190:193], v[108:111]
	v_mfma_f32_16x16x32_bf16 v[92:95], v[128:131], v[198:201], v[92:95]
	v_mfma_f32_16x16x32_bf16 v[88:91], v[136:139], v[198:201], v[88:91]
	v_mfma_f32_16x16x32_bf16 v[72:75], v[136:139], v[206:209], v[72:75]
	v_mfma_f32_16x16x32_bf16 v[76:79], v[128:131], v[206:209], v[76:79]
	s_setprio 0
	s_setprio 1
	v_mfma_f32_16x16x32_bf16 v[124:127], v[132:135], v[186:189], v[124:127]
	v_mfma_f32_16x16x32_bf16 v[120:123], v[140:143], v[186:189], v[120:123]
	v_mfma_f32_16x16x32_bf16 v[104:107], v[140:143], v[194:197], v[104:107]
	v_mfma_f32_16x16x32_bf16 v[108:111], v[132:135], v[194:197], v[108:111]
	v_mfma_f32_16x16x32_bf16 v[92:95], v[132:135], v[202:205], v[92:95]
	v_mfma_f32_16x16x32_bf16 v[88:91], v[140:143], v[202:205], v[88:91]
	v_mfma_f32_16x16x32_bf16 v[72:75], v[140:143], v[210:213], v[72:75]
	v_mfma_f32_16x16x32_bf16 v[76:79], v[132:135], v[210:213], v[76:79]
	s_setprio 0
	s_setprio 1
	v_mfma_f32_16x16x32_bf16 v[116:119], v[150:153], v[182:185], v[116:119]
	v_mfma_f32_16x16x32_bf16 v[112:115], v[158:161], v[182:185], v[112:115]
	v_mfma_f32_16x16x32_bf16 v[96:99], v[158:161], v[190:193], v[96:99]
	v_mfma_f32_16x16x32_bf16 v[100:103], v[150:153], v[190:193], v[100:103]
	v_mfma_f32_16x16x32_bf16 v[84:87], v[150:153], v[198:201], v[84:87]
	v_mfma_f32_16x16x32_bf16 v[80:83], v[158:161], v[198:201], v[80:83]
	v_mfma_f32_16x16x32_bf16 v[64:67], v[158:161], v[206:209], v[64:67]
	v_mfma_f32_16x16x32_bf16 v[68:71], v[150:153], v[206:209], v[68:71]
	s_setprio 0
	s_setprio 1
	v_mfma_f32_16x16x32_bf16 v[116:119], v[154:157], v[186:189], v[116:119]
	v_mfma_f32_16x16x32_bf16 v[112:115], v[162:165], v[186:189], v[112:115]
	v_mfma_f32_16x16x32_bf16 v[96:99], v[162:165], v[194:197], v[96:99]
	v_mfma_f32_16x16x32_bf16 v[100:103], v[154:157], v[194:197], v[100:103]
	v_mfma_f32_16x16x32_bf16 v[84:87], v[154:157], v[202:205], v[84:87]
	v_mfma_f32_16x16x32_bf16 v[80:83], v[162:165], v[202:205], v[80:83]
	v_mfma_f32_16x16x32_bf16 v[64:67], v[162:165], v[210:213], v[64:67]
	v_mfma_f32_16x16x32_bf16 v[68:71], v[154:157], v[210:213], v[68:71]
	s_setprio 0
	s_barrier
	v_mov_b32_e32 v144, v169
	s_add_i32 s16, s94, s86
	ds_read_b128 v[182:185], v177 offset:16384
	ds_read_b128 v[186:189], v177 offset:17408
	ds_read_b128 v[190:193], v177 offset:18432
	ds_read_b128 v[194:197], v177 offset:19456
	ds_read_b128 v[198:201], v177 offset:20480
	ds_read_b128 v[202:205], v177 offset:21504
	ds_read_b128 v[206:209], v177 offset:22528
	ds_read_b128 v[210:213], v177 offset:23552
	s_mov_b32 m0, s16
	s_nop 0
	global_load_lds_dwordx4 v144, s[52:53]
	v_mov_b32_e32 v144, v171
	s_add_i32 m0, s16, 0x2000
	s_add_u32 s60, s52, 0x40000
	global_load_lds_dwordx4 v144, s[52:53]
	s_addc_u32 s61, s53, 0
	v_mov_b32_e32 v144, v169
	s_add_i32 s16, s95, s86
	s_mov_b32 m0, s16
	s_nop 0
	global_load_lds_dwordx4 v144, s[60:61]
	v_mov_b32_e32 v144, v171
	s_add_i32 m0, s16, 0x2000
	s_nop 0
	global_load_lds_dwordx4 v144, s[60:61]
	v_mov_b32_e32 v144, v168
	s_mov_b32 m0, s87
	s_nop 0
	global_load_lds_dwordx4 v144, s[50:51]
	v_mov_b32_e32 v144, v170
	s_mov_b32 m0, s88
	s_nop 0
	global_load_lds_dwordx4 v144, s[50:51]
	s_waitcnt vmcnt(8)
	s_waitcnt lgkmcnt(0)
	s_barrier
; #define PG8_LDA(dst, b, h) do { if constexpr (FP8) { _Pragma("unroll") for (int m = 0; m < 4; ++m) dst##8[m] = PG8_LD8(PG8_SA(b, h), aoff, aoff1, m); } \
;         else { _Pragma("unroll") for (int m = 0; m < 4; ++m) _Pragma("unroll") for (int k = 0; k < 2; ++k) dst[m][k] = *(const LAS bf16x8*)(lds + PG8_SA(b, h) + (k ? aoff1 : aoff) + m * 2048); } } while (0)
; #define PG8_LDB(dst, b, h) do { if constexpr (FP8) { dst##8[0] = PG8_LD8(PG8_SB(b, h), boff, boff1, 0); dst##8[1] = PG8_LD8(PG8_SB(b, h), boff, boff1, 1); } \
;         else { _Pragma("unroll") for (int n = 0; n < 2; ++n) _Pragma("unroll") for (int k = 0; k < 2; ++k) dst[n][k] = *(const LAS bf16x8*)(lds + PG8_SB(b, h) + (k ? boff1 : boff) + n * 2048); } } while (0)
; #define PG8_WAIT_V(n) asm volatile("s_waitcnt vmcnt(" #n ")" ::: "memory")
; #define PG8_WAIT_L(n) asm volatile("s_waitcnt lgkmcnt(" #n ")" ::: "memory")
; #define PG8_BAR __builtin_amdgcn_s_barrier()
; #define PG8_SCHED __builtin_amdgcn_sched_barrier(0)
; #define PG8_S3 PG8_STAGE(PG8_SA(0, 1), a2 + hstepA, voffA)
; template <class Epi, class SchedT, bool ALIGN_EPI, bool SP2, bool FP8 = false>
; __device__ __forceinline__ void gemm_phase(LAS unsigned char* lds, const Gemm g, const SchedT& S, const Epi& E, const int wid) {
;     ...
;             PG8_WAIT_V(8); PG8_WAIT_L(0); PG8_BAR; PG8_MMAP(1, 0, 1); PG8_BAR; PG8_SCHED;
;             PG8_LDB(B0, 1, 0); PG8_LDB(B1, 1, 1); PG8_SCHED; PG8_LDA(At, 1, 0); PG8_S3;
;             PG8_WAIT_V(8); PG8_WAIT_L(0); PG8_BAR; PG8_MMAP(0, 1, 0); PG8_BAR; PG8_SCHED;
	s_setprio 1
	s_waitcnt lgkmcnt(0)
	v_mfma_f32_16x16x32_bf16 v[60:63], v[128:131], v[182:185], v[60:63]
	v_mfma_f32_16x16x32_bf16 v[56:59], v[136:139], v[182:185], v[56:59]
	v_mfma_f32_16x16x32_bf16 v[40:43], v[136:139], v[190:193], v[40:43]
	v_mfma_f32_16x16x32_bf16 v[44:47], v[128:131], v[190:193], v[44:47]
	v_mfma_f32_16x16x32_bf16 v[28:31], v[128:131], v[198:201], v[28:31]
	v_mfma_f32_16x16x32_bf16 v[24:27], v[136:139], v[198:201], v[24:27]
	v_mfma_f32_16x16x32_bf16 v[8:11], v[136:139], v[206:209], v[8:11]
	v_mfma_f32_16x16x32_bf16 v[12:15], v[128:131], v[206:209], v[12:15]
	s_setprio 0
	s_setprio 1
	v_mfma_f32_16x16x32_bf16 v[60:63], v[132:135], v[186:189], v[60:63]
	v_mfma_f32_16x16x32_bf16 v[56:59], v[140:143], v[186:189], v[56:59]
	v_mfma_f32_16x16x32_bf16 v[40:43], v[140:143], v[194:197], v[40:43]
	v_mfma_f32_16x16x32_bf16 v[44:47], v[132:135], v[194:197], v[44:47]
	v_mfma_f32_16x16x32_bf16 v[28:31], v[132:135], v[202:205], v[28:31]
	v_mfma_f32_16x16x32_bf16 v[24:27], v[140:143], v[202:205], v[24:27]
	v_mfma_f32_16x16x32_bf16 v[8:11], v[140:143], v[210:213], v[8:11]
	v_mfma_f32_16x16x32_bf16 v[12:15], v[132:135], v[210:213], v[12:15]
	s_setprio 0
	s_setprio 1
	v_mfma_f32_16x16x32_bf16 v[52:55], v[150:153], v[182:185], v[52:55]
	v_mfma_f32_16x16x32_bf16 v[48:51], v[158:161], v[182:185], v[48:51]
	v_mfma_f32_16x16x32_bf16 v[32:35], v[158:161], v[190:193], v[32:35]
	v_mfma_f32_16x16x32_bf16 v[36:39], v[150:153], v[190:193], v[36:39]
	v_mfma_f32_16x16x32_bf16 v[20:23], v[150:153], v[198:201], v[20:23]
	v_mfma_f32_16x16x32_bf16 v[16:19], v[158:161], v[198:201], v[16:19]
	v_mfma_f32_16x16x32_bf16 v[0:3], v[158:161], v[206:209], v[0:3]
	v_mfma_f32_16x16x32_bf16 v[4:7], v[150:153], v[206:209], v[4:7]
	s_setprio 0
	s_setprio 1
	v_mfma_f32_16x16x32_bf16 v[52:55], v[154:157], v[186:189], v[52:55]
	v_mfma_f32_16x16x32_bf16 v[48:51], v[162:165], v[186:189], v[48:51]
	v_mfma_f32_16x16x32_bf16 v[32:35], v[162:165], v[194:197], v[32:35]
	v_mfma_f32_16x16x32_bf16 v[36:39], v[154:157], v[194:197], v[36:39]
	v_mfma_f32_16x16x32_bf16 v[20:23], v[154:157], v[202:205], v[20:23]
	v_mfma_f32_16x16x32_bf16 v[16:19], v[162:165], v[202:205], v[16:19]
	v_mfma_f32_16x16x32_bf16 v[0:3], v[162:165], v[210:213], v[0:3]
	v_mfma_f32_16x16x32_bf16 v[4:7], v[154:157], v[210:213], v[4:7]
	s_setprio 0
	s_barrier
	s_add_i32 s16, 0, 0x18000
	s_add_i32 s17, 0, 0x1c000
	v_add_u32_e32 v132, s16, v172
	v_add_u32_e32 v144, s17, v172
	ds_read_b128 v[128:131], v132
	ds_read_b128 v[132:135], v132 offset:1024
	ds_read_b128 v[136:139], v178
	ds_read_b128 v[140:143], v178 offset:1024
	ds_read_b128 v[150:153], v144
	ds_read_b128 v[154:157], v144 offset:1024
	ds_read_b128 v[158:161], v179
	ds_read_b128 v[162:165], v179 offset:1024
	s_add_u32 s60, s50, 0x40000
	v_mov_b32_e32 v144, v168
	s_mov_b32 m0, s89
	ds_read_b128 v[182:185], v177 offset:32768
	ds_read_b128 v[186:189], v177 offset:33792
	ds_read_b128 v[190:193], v177 offset:34816
	ds_read_b128 v[194:197], v177 offset:35840
	ds_read_b128 v[198:201], v177 offset:36864
	ds_read_b128 v[202:205], v177 offset:37888
	ds_read_b128 v[206:209], v177 offset:38912
	ds_read_b128 v[210:213], v177 offset:39936
	s_addc_u32 s61, s51, 0
	s_nop 0
	global_load_lds_dwordx4 v144, s[60:61]
	v_mov_b32_e32 v144, v170
	s_mov_b32 m0, s90
	s_nop 0
	global_load_lds_dwordx4 v144, s[60:61]
	s_waitcnt vmcnt(8)
	s_waitcnt lgkmcnt(0)
	s_barrier
	s_setprio 1
	s_waitcnt lgkmcnt(0)
	v_mfma_f32_16x16x32_bf16 v[124:127], v[128:131], v[182:185], v[124:127]
	v_mfma_f32_16x16x32_bf16 v[120:123], v[136:139], v[182:185], v[120:123]
	v_mfma_f32_16x16x32_bf16 v[104:107], v[136:139], v[190:193], v[104:107]
	v_mfma_f32_16x16x32_bf16 v[108:111], v[128:131], v[190:193], v[108:111]
	v_mfma_f32_16x16x32_bf16 v[92:95], v[128:131], v[198:201], v[92:95]
	v_mfma_f32_16x16x32_bf16 v[88:91], v[136:139], v[198:201], v[88:91]
	v_mfma_f32_16x16x32_bf16 v[72:75], v[136:139], v[206:209], v[72:75]
	v_mfma_f32_16x16x32_bf16 v[76:79], v[128:131], v[206:209], v[76:79]
	s_setprio 0
	s_setprio 1
	v_mfma_f32_16x16x32_bf16 v[124:127], v[132:135], v[186:189], v[124:127]
	v_mfma_f32_16x16x32_bf16 v[120:123], v[140:143], v[186:189], v[120:123]
	v_mfma_f32_16x16x32_bf16 v[104:107], v[140:143], v[194:197], v[104:107]
	v_mfma_f32_16x16x32_bf16 v[108:111], v[132:135], v[194:197], v[108:111]
	v_mfma_f32_16x16x32_bf16 v[92:95], v[132:135], v[202:205], v[92:95]
	v_mfma_f32_16x16x32_bf16 v[88:91], v[140:143], v[202:205], v[88:91]
	v_mfma_f32_16x16x32_bf16 v[72:75], v[140:143], v[210:213], v[72:75]
	v_mfma_f32_16x16x32_bf16 v[76:79], v[132:135], v[210:213], v[76:79]
	s_setprio 0
	s_setprio 1
	v_mfma_f32_16x16x32_bf16 v[116:119], v[150:153], v[182:185], v[116:119]
	v_mfma_f32_16x16x32_bf16 v[112:115], v[158:161], v[182:185], v[112:115]
	v_mfma_f32_16x16x32_bf16 v[96:99], v[158:161], v[190:193], v[96:99]
	v_mfma_f32_16x16x32_bf16 v[100:103], v[150:153], v[190:193], v[100:103]
	v_mfma_f32_16x16x32_bf16 v[84:87], v[150:153], v[198:201], v[84:87]
	v_mfma_f32_16x16x32_bf16 v[80:83], v[158:161], v[198:201], v[80:83]
	v_mfma_f32_16x16x32_bf16 v[64:67], v[158:161], v[206:209], v[64:67]
	v_mfma_f32_16x16x32_bf16 v[68:71], v[150:153], v[206:209], v[68:71]
	s_setprio 0
	s_setprio 1
	v_mfma_f32_16x16x32_bf16 v[116:119], v[154:157], v[186:189], v[116:119]
	v_mfma_f32_16x16x32_bf16 v[112:115], v[162:165], v[186:189], v[112:115]
	v_mfma_f32_16x16x32_bf16 v[96:99], v[162:165], v[194:197], v[96:99]
	v_mfma_f32_16x16x32_bf16 v[100:103], v[154:157], v[194:197], v[100:103]
	v_mfma_f32_16x16x32_bf16 v[84:87], v[154:157], v[202:205], v[84:87]
	v_mfma_f32_16x16x32_bf16 v[80:83], v[162:165], v[202:205], v[80:83]
	v_mfma_f32_16x16x32_bf16 v[64:67], v[162:165], v[210:213], v[64:67]
	v_mfma_f32_16x16x32_bf16 v[68:71], v[154:157], v[210:213], v[68:71]
	s_setprio 0
	s_barrier
; #define PG8_LDA(dst, b, h) do { if constexpr (FP8) { _Pragma("unroll") for (int m = 0; m < 4; ++m) dst##8[m] = PG8_LD8(PG8_SA(b, h), aoff, aoff1, m); } \
;         else { _Pragma("unroll") for (int m = 0; m < 4; ++m) _Pragma("unroll") for (int k = 0; k < 2; ++k) dst[m][k] = *(const LAS bf16x8*)(lds + PG8_SA(b, h) + (k ? aoff1 : aoff) + m * 2048); } } while (0)
; #define PG8_LDB(dst, b, h) do { if constexpr (FP8) { dst##8[0] = PG8_LD8(PG8_SB(b, h), boff, boff1, 0); dst##8[1] = PG8_LD8(PG8_SB(b, h), boff, boff1, 1); } \
;         else { _Pragma("unroll") for (int n = 0; n < 2; ++n) _Pragma("unroll") for (int k = 0; k < 2; ++k) dst[n][k] = *(const LAS bf16x8*)(lds + PG8_SB(b, h) + (k ? boff1 : boff) + n * 2048); } } while (0)
; #define PG8_WAIT_V(n) asm volatile("s_waitcnt vmcnt(" #n ")" ::: "memory")
; #define PG8_WAIT_L(n) asm volatile("s_waitcnt lgkmcnt(" #n ")" ::: "memory")
; #define PG8_BAR __builtin_amdgcn_s_barrier()
; #define PG8_SCHED __builtin_amdgcn_sched_barrier(0)
; #define PG8_S1 PG8_STAGE(PG8_SA(1, 1), a1 + hstepA, voffA)
; #define PG8_S3 PG8_STAGE(PG8_SA(0, 1), a2 + hstepA, voffA)
; template <class Epi, class SchedT, bool ALIGN_EPI, bool SP2, bool FP8 = false>
; __device__ __forceinline__ void gemm_phase(LAS unsigned char* lds, const Gemm g, const SchedT& S, const Epi& E, const int wid) {
;     ...
;         for (int t = 0; t < nt; t += 2) {
;             const bool last = (t == nt - 2);
;             const char* a1 = cA + (size_t)(t + 1) * kstep;
;             const char* a2 = last ? nA : cA + (size_t)(t + 2) * kstep; const char* b2 = last ? nB : cB + (size_t)(t + 2) * kstep;
;             const char* a3 = a2 + kstep; const char* b3 = b2 + kstep;
;     ...
;             PG8_LDB(B0, 0, 0); PG8_LDB(B1, 0, 1); PG8_SCHED; PG8_LDA(At, 0, 0); PG8_S1;
;             PG8_WAIT_V(8); PG8_WAIT_L(0); PG8_BAR; PG8_MMAP(0, 0, 0); PG8_BAR; PG8_SCHED;
;             PG8_LDA(At, 0, 1); PG8_S2;
;             PG8_WAIT_V(8); PG8_WAIT_L(0); PG8_BAR; PG8_MMAP(1, 0, 1); PG8_BAR; PG8_SCHED;
;             PG8_LDB(B0, 1, 0); PG8_LDB(B1, 1, 1); PG8_SCHED; PG8_LDA(At, 1, 0); PG8_S3;
;             PG8_WAIT_V(8); PG8_WAIT_L(0); PG8_BAR; PG8_MMAP(0, 1, 0); PG8_BAR; PG8_SCHED;
;             PG8_LDA(At, 1, 1); PG8_S4;
;             PG8_WAIT_V(8); PG8_WAIT_L(0); PG8_BAR; PG8_MMAP(1, 1, 1); PG8_BAR; PG8_SCHED;
	v_mov_b32_e32 v144, v169
	ds_read_b128 v[182:185], v177 offset:49152
	ds_read_b128 v[186:189], v177 offset:50176
	ds_read_b128 v[190:193], v177 offset:51200
	ds_read_b128 v[194:197], v177 offset:52224
	ds_read_b128 v[198:201], v177 offset:53248
	ds_read_b128 v[202:205], v177 offset:54272
	ds_read_b128 v[206:209], v177 offset:55296
	ds_read_b128 v[210:213], v177 offset:56320
	s_add_i32 s16, s16, s86
	v_lshl_add_u64 v[166:167], s[52:53], 0, v[144:145]
	v_lshl_add_u64 v[166:167], v[166:167], 0, s[6:7]
	s_mov_b32 m0, s16
	v_mov_b32_e32 v144, v171
	global_load_lds_dwordx4 v[166:167], off
	s_add_i32 m0, s16, 0x2000
	s_nop 0
	v_lshl_add_u64 v[166:167], s[52:53], 0, v[144:145]
	s_add_u32 s52, s52, 0x40080
	v_lshl_add_u64 v[166:167], v[166:167], 0, s[6:7]
	s_addc_u32 s53, s53, 0
	v_mov_b32_e32 v144, v169
	s_add_i32 s16, s17, s86
	global_load_lds_dwordx4 v[166:167], off
	s_mov_b32 m0, s16
	s_nop 0
	global_load_lds_dwordx4 v144, s[52:53]
	v_mov_b32_e32 v144, v171
	s_add_i32 m0, s16, 0x2000
	s_nop 0
	global_load_lds_dwordx4 v144, s[52:53]
	v_mov_b32_e32 v144, v168
	s_mov_b32 m0, s92
	v_lshl_add_u64 v[166:167], s[50:51], 0, v[144:145]
	v_lshl_add_u64 v[166:167], v[166:167], 0, s[6:7]
	v_mov_b32_e32 v144, v170
	global_load_lds_dwordx4 v[166:167], off
	s_mov_b32 m0, s93
	v_lshl_add_u64 v[166:167], s[50:51], 0, v[144:145]
	v_lshl_add_u64 v[166:167], v[166:167], 0, s[6:7]
	global_load_lds_dwordx4 v[166:167], off
	s_waitcnt vmcnt(8)
	s_waitcnt lgkmcnt(0)
	s_barrier
	s_setprio 1
	s_waitcnt lgkmcnt(0)
	v_mfma_f32_16x16x32_bf16 v[60:63], v[128:131], v[182:185], v[60:63]
	v_mfma_f32_16x16x32_bf16 v[56:59], v[136:139], v[182:185], v[56:59]
	v_mfma_f32_16x16x32_bf16 v[40:43], v[136:139], v[190:193], v[40:43]
	v_mfma_f32_16x16x32_bf16 v[44:47], v[128:131], v[190:193], v[44:47]
	v_mfma_f32_16x16x32_bf16 v[28:31], v[128:131], v[198:201], v[28:31]
	v_mfma_f32_16x16x32_bf16 v[24:27], v[136:139], v[198:201], v[24:27]
	v_mfma_f32_16x16x32_bf16 v[8:11], v[136:139], v[206:209], v[8:11]
	v_mfma_f32_16x16x32_bf16 v[12:15], v[128:131], v[206:209], v[12:15]
	s_setprio 0
	s_setprio 1
	v_mfma_f32_16x16x32_bf16 v[60:63], v[132:135], v[186:189], v[60:63]
	v_mfma_f32_16x16x32_bf16 v[56:59], v[140:143], v[186:189], v[56:59]
	v_mfma_f32_16x16x32_bf16 v[40:43], v[140:143], v[194:197], v[40:43]
	v_mfma_f32_16x16x32_bf16 v[44:47], v[132:135], v[194:197], v[44:47]
	v_mfma_f32_16x16x32_bf16 v[28:31], v[132:135], v[202:205], v[28:31]
	v_mfma_f32_16x16x32_bf16 v[24:27], v[140:143], v[202:205], v[24:27]
	v_mfma_f32_16x16x32_bf16 v[8:11], v[140:143], v[210:213], v[8:11]
	v_mfma_f32_16x16x32_bf16 v[12:15], v[132:135], v[210:213], v[12:15]
	s_setprio 0
	s_setprio 1
	v_mfma_f32_16x16x32_bf16 v[52:55], v[150:153], v[182:185], v[52:55]
	v_mfma_f32_16x16x32_bf16 v[48:51], v[158:161], v[182:185], v[48:51]
	v_mfma_f32_16x16x32_bf16 v[32:35], v[158:161], v[190:193], v[32:35]
	v_mfma_f32_16x16x32_bf16 v[36:39], v[150:153], v[190:193], v[36:39]
	v_mfma_f32_16x16x32_bf16 v[20:23], v[150:153], v[198:201], v[20:23]
	v_mfma_f32_16x16x32_bf16 v[16:19], v[158:161], v[198:201], v[16:19]
	v_mfma_f32_16x16x32_bf16 v[0:3], v[158:161], v[206:209], v[0:3]
	v_mfma_f32_16x16x32_bf16 v[4:7], v[150:153], v[206:209], v[4:7]
	s_setprio 0
	s_setprio 1
	v_mfma_f32_16x16x32_bf16 v[52:55], v[154:157], v[186:189], v[52:55]
	v_mfma_f32_16x16x32_bf16 v[48:51], v[162:165], v[186:189], v[48:51]
	v_mfma_f32_16x16x32_bf16 v[32:35], v[162:165], v[194:197], v[32:35]
	v_mfma_f32_16x16x32_bf16 v[36:39], v[154:157], v[194:197], v[36:39]
	v_mfma_f32_16x16x32_bf16 v[20:23], v[154:157], v[202:205], v[20:23]
	v_mfma_f32_16x16x32_bf16 v[16:19], v[162:165], v[202:205], v[16:19]
	v_mfma_f32_16x16x32_bf16 v[0:3], v[162:165], v[210:213], v[0:3]
	v_mfma_f32_16x16x32_bf16 v[4:7], v[154:157], v[210:213], v[4:7]
	s_setprio 0
	s_barrier
	s_add_u32 s48, s48, 0x100
	s_addc_u32 s49, s49, 0
	s_add_u32 s30, s30, 0x100
	s_addc_u32 s31, s31, 0
	s_cmp_ge_i32 s35, s20
	s_mov_b32 s34, s35
	s_cbranch_scc0 .LBB0_899
	s_branch .LBB0_894

; #define PG8_LDA(dst, b, h) do { if constexpr (FP8) { _Pragma("unroll") for (int m = 0; m < 4; ++m) dst##8[m] = PG8_LD8(PG8_SA(b, h), aoff, aoff1, m); } \
;         else { _Pragma("unroll") for (int m = 0; m < 4; ++m) _Pragma("unroll") for (int k = 0; k < 2; ++k) dst[m][k] = *(const LAS bf16x8*)(lds + PG8_SA(b, h) + (k ? aoff1 : aoff) + m * 2048); } } while (0)
; #define PG8_LDB(dst, b, h) do { if constexpr (FP8) { dst##8[0] = PG8_LD8(PG8_SB(b, h), boff, boff1, 0); dst##8[1] = PG8_LD8(PG8_SB(b, h), boff, boff1, 1); } \
;         else { _Pragma("unroll") for (int n = 0; n < 2; ++n) _Pragma("unroll") for (int k = 0; k < 2; ++k) dst[n][k] = *(const LAS bf16x8*)(lds + PG8_SB(b, h) + (k ? boff1 : boff) + n * 2048); } } while (0)
; #define PG8_WAIT_V(n) asm volatile("s_waitcnt vmcnt(" #n ")" ::: "memory")
; #define PG8_WAIT_L(n) asm volatile("s_waitcnt lgkmcnt(" #n ")" ::: "memory")
; #define PG8_BAR __builtin_amdgcn_s_barrier()
; #define PG8_SCHED __builtin_amdgcn_sched_barrier(0)
; #define PG8_S1 PG8_STAGE(PG8_SA(1, 1), a1 + hstepA, voffA)
; #define PG8_S2 do { PG8_STAGE(PG8_SB(0, 0), b2, voffB); PG8_STAGE(PG8_SB(0, 1), b2 + hstepB, voffB); PG8_STAGE(PG8_SA(0, 0), a2, voffA); } while (0)
; template <class Epi, class SchedT, bool ALIGN_EPI, bool SP2, bool FP8 = false>
; __device__ __forceinline__ void gemm_phase(LAS unsigned char* lds, const Gemm g, const SchedT& S, const Epi& E, const int wid) {
;     ...
;             const bool last = (t == nt - 2);
;             const char* a1 = cA + (size_t)(t + 1) * kstep;
;             const char* a2 = last ? nA : cA + (size_t)(t + 2) * kstep; const char* b2 = last ? nB : cB + (size_t)(t + 2) * kstep;
;             const char* a3 = a2 + kstep; const char* b3 = b2 + kstep;
;     ...
;             PG8_LDB(B0, 0, 0); PG8_LDB(B1, 0, 1); PG8_SCHED; PG8_LDA(At, 0, 0); PG8_S1;
;             PG8_WAIT_V(8); PG8_WAIT_L(0); PG8_BAR; PG8_MMAP(0, 0, 0); PG8_BAR; PG8_SCHED;
;             PG8_LDA(At, 0, 1); PG8_S2;
;             PG8_WAIT_V(8); PG8_WAIT_L(0); PG8_BAR; PG8_MMAP(1, 0, 1); PG8_BAR; PG8_SCHED;
.LBB0_970:
	ds_read_b128 v[134:137], v175
	ds_read_b128 v[138:141], v175 offset:1024
	ds_read_b128 v[142:145], v176
	ds_read_b128 v[146:149], v176 offset:1024
	ds_read_b128 v[150:153], v177
	ds_read_b128 v[154:157], v177 offset:1024
	ds_read_b128 v[158:161], v178
	ds_read_b128 v[162:165], v178 offset:1024
	s_add_i32 s48, s34, 2
	s_add_u32 s16, s24, 0xfff00080
	s_addc_u32 s17, s25, -1
	s_cmp_eq_u32 s45, s34
	s_cselect_b32 s34, s15, s16
	s_cselect_b32 s35, s13, s17
	s_cselect_b32 s39, s27, s47
	s_cselect_b32 s38, s31, s46
	v_mov_b32_e32 v128, v172
	ds_read_b128 v[166:169], v179
	ds_read_b128 v[184:187], v179 offset:1024
	ds_read_b128 v[188:191], v179 offset:2048
	ds_read_b128 v[192:195], v179 offset:3072
	ds_read_b128 v[196:199], v179 offset:4096
	ds_read_b128 v[200:203], v179 offset:5120
	ds_read_b128 v[204:207], v179 offset:6144
	ds_read_b128 v[208:211], v179 offset:7168
	s_add_i32 m0, s87, 0xc000
	s_nop 0
	global_load_lds_dwordx4 v128, s[24:25]
	v_mov_b32_e32 v128, v173
	s_add_i32 m0, s87, 0xe000
	s_nop 0
	global_load_lds_dwordx4 v128, s[24:25]
	s_waitcnt vmcnt(8)
	s_waitcnt lgkmcnt(0)
	s_barrier
	s_setprio 1
	s_waitcnt lgkmcnt(0)
	v_mfma_f32_16x16x32_bf16 v[124:127], v[134:137], v[166:169], v[124:127]
	v_mfma_f32_16x16x32_bf16 v[120:123], v[142:145], v[166:169], v[120:123]
	v_mfma_f32_16x16x32_bf16 v[104:107], v[142:145], v[188:191], v[104:107]
	v_mfma_f32_16x16x32_bf16 v[108:111], v[134:137], v[188:191], v[108:111]
	v_mfma_f32_16x16x32_bf16 v[92:95], v[134:137], v[196:199], v[92:95]
	v_mfma_f32_16x16x32_bf16 v[88:91], v[142:145], v[196:199], v[88:91]
	v_mfma_f32_16x16x32_bf16 v[72:75], v[142:145], v[204:207], v[72:75]
	v_mfma_f32_16x16x32_bf16 v[76:79], v[134:137], v[204:207], v[76:79]
	s_setprio 0
	s_setprio 1
	v_mfma_f32_16x16x32_bf16 v[124:127], v[138:141], v[184:187], v[124:127]
	v_mfma_f32_16x16x32_bf16 v[120:123], v[146:149], v[184:187], v[120:123]
	v_mfma_f32_16x16x32_bf16 v[104:107], v[146:149], v[192:195], v[104:107]
	v_mfma_f32_16x16x32_bf16 v[108:111], v[138:141], v[192:195], v[108:111]
	v_mfma_f32_16x16x32_bf16 v[92:95], v[138:141], v[200:203], v[92:95]
	v_mfma_f32_16x16x32_bf16 v[88:91], v[146:149], v[200:203], v[88:91]
	v_mfma_f32_16x16x32_bf16 v[72:75], v[146:149], v[208:211], v[72:75]
	v_mfma_f32_16x16x32_bf16 v[76:79], v[138:141], v[208:211], v[76:79]
	s_setprio 0
	s_setprio 1
	v_mfma_f32_16x16x32_bf16 v[116:119], v[150:153], v[166:169], v[116:119]
	v_mfma_f32_16x16x32_bf16 v[112:115], v[158:161], v[166:169], v[112:115]
	v_mfma_f32_16x16x32_bf16 v[96:99], v[158:161], v[188:191], v[96:99]
	v_mfma_f32_16x16x32_bf16 v[100:103], v[150:153], v[188:191], v[100:103]
	v_mfma_f32_16x16x32_bf16 v[84:87], v[150:153], v[196:199], v[84:87]
	v_mfma_f32_16x16x32_bf16 v[80:83], v[158:161], v[196:199], v[80:83]
	v_mfma_f32_16x16x32_bf16 v[64:67], v[158:161], v[204:207], v[64:67]
	v_mfma_f32_16x16x32_bf16 v[68:71], v[150:153], v[204:207], v[68:71]
	s_setprio 0
	s_setprio 1
	v_mfma_f32_16x16x32_bf16 v[116:119], v[154:157], v[184:187], v[116:119]
	v_mfma_f32_16x16x32_bf16 v[112:115], v[162:165], v[184:187], v[112:115]
	v_mfma_f32_16x16x32_bf16 v[96:99], v[162:165], v[192:195], v[96:99]
	v_mfma_f32_16x16x32_bf16 v[100:103], v[154:157], v[192:195], v[100:103]
	v_mfma_f32_16x16x32_bf16 v[84:87], v[154:157], v[200:203], v[84:87]
	v_mfma_f32_16x16x32_bf16 v[80:83], v[162:165], v[200:203], v[80:83]
	v_mfma_f32_16x16x32_bf16 v[64:67], v[162:165], v[208:211], v[64:67]
	v_mfma_f32_16x16x32_bf16 v[68:71], v[154:157], v[208:211], v[68:71]
	s_setprio 0
	s_barrier
	v_mov_b32_e32 v128, v172
	s_add_i32 s16, s94, s86
	ds_read_b128 v[166:169], v179 offset:16384
	ds_read_b128 v[184:187], v179 offset:17408
	ds_read_b128 v[188:191], v179 offset:18432
	ds_read_b128 v[192:195], v179 offset:19456
	ds_read_b128 v[196:199], v179 offset:20480
	ds_read_b128 v[200:203], v179 offset:21504
	ds_read_b128 v[204:207], v179 offset:22528
	ds_read_b128 v[208:211], v179 offset:23552
	s_mov_b32 m0, s16
	s_nop 0
	global_load_lds_dwordx4 v128, s[38:39]
	v_mov_b32_e32 v128, v173
	s_add_i32 m0, s16, 0x2000
	s_add_u32 s50, s38, 0x100000
	global_load_lds_dwordx4 v128, s[38:39]
	s_addc_u32 s51, s39, 0
	v_mov_b32_e32 v128, v172
	s_add_i32 s16, s95, s86
	s_mov_b32 m0, s16
	s_nop 0
	global_load_lds_dwordx4 v128, s[50:51]
	v_mov_b32_e32 v128, v173
	s_add_i32 m0, s16, 0x2000
	s_nop 0
	global_load_lds_dwordx4 v128, s[50:51]
	v_mov_b32_e32 v128, v172
	s_mov_b32 m0, s87
	s_nop 0
	global_load_lds_dwordx4 v128, s[34:35]
	v_mov_b32_e32 v128, v173
	s_mov_b32 m0, s88
	s_nop 0
	global_load_lds_dwordx4 v128, s[34:35]
	s_waitcnt vmcnt(8)
	s_waitcnt lgkmcnt(0)
	s_barrier
; #define PG8_LDA(dst, b, h) do { if constexpr (FP8) { _Pragma("unroll") for (int m = 0; m < 4; ++m) dst##8[m] = PG8_LD8(PG8_SA(b, h), aoff, aoff1, m); } \
;         else { _Pragma("unroll") for (int m = 0; m < 4; ++m) _Pragma("unroll") for (int k = 0; k < 2; ++k) dst[m][k] = *(const LAS bf16x8*)(lds + PG8_SA(b, h) + (k ? aoff1 : aoff) + m * 2048); } } while (0)
; #define PG8_LDB(dst, b, h) do { if constexpr (FP8) { dst##8[0] = PG8_LD8(PG8_SB(b, h), boff, boff1, 0); dst##8[1] = PG8_LD8(PG8_SB(b, h), boff, boff1, 1); } \
;         else { _Pragma("unroll") for (int n = 0; n < 2; ++n) _Pragma("unroll") for (int k = 0; k < 2; ++k) dst[n][k] = *(const LAS bf16x8*)(lds + PG8_SB(b, h) + (k ? boff1 : boff) + n * 2048); } } while (0)
; #define PG8_WAIT_V(n) asm volatile("s_waitcnt vmcnt(" #n ")" ::: "memory")
; #define PG8_WAIT_L(n) asm volatile("s_waitcnt lgkmcnt(" #n ")" ::: "memory")
; #define PG8_BAR __builtin_amdgcn_s_barrier()
; #define PG8_SCHED __builtin_amdgcn_sched_barrier(0)
; #define PG8_S3 PG8_STAGE(PG8_SA(0, 1), a2 + hstepA, voffA)
; template <class Epi, class SchedT, bool ALIGN_EPI, bool SP2, bool FP8 = false>
; __device__ __forceinline__ void gemm_phase(LAS unsigned char* lds, const Gemm g, const SchedT& S, const Epi& E, const int wid) {
;     ...
;             PG8_WAIT_V(8); PG8_WAIT_L(0); PG8_BAR; PG8_MMAP(1, 0, 1); PG8_BAR; PG8_SCHED;
;             PG8_LDB(B0, 1, 0); PG8_LDB(B1, 1, 1); PG8_SCHED; PG8_LDA(At, 1, 0); PG8_S3;
;             PG8_WAIT_V(8); PG8_WAIT_L(0); PG8_BAR; PG8_MMAP(0, 1, 0); PG8_BAR; PG8_SCHED;
	s_setprio 1
	s_waitcnt lgkmcnt(0)
	v_mfma_f32_16x16x32_bf16 v[60:63], v[134:137], v[166:169], v[60:63]
	v_mfma_f32_16x16x32_bf16 v[56:59], v[142:145], v[166:169], v[56:59]
	v_mfma_f32_16x16x32_bf16 v[40:43], v[142:145], v[188:191], v[40:43]
	v_mfma_f32_16x16x32_bf16 v[44:47], v[134:137], v[188:191], v[44:47]
	v_mfma_f32_16x16x32_bf16 v[28:31], v[134:137], v[196:199], v[28:31]
	v_mfma_f32_16x16x32_bf16 v[24:27], v[142:145], v[196:199], v[24:27]
	v_mfma_f32_16x16x32_bf16 v[8:11], v[142:145], v[204:207], v[8:11]
	v_mfma_f32_16x16x32_bf16 v[12:15], v[134:137], v[204:207], v[12:15]
	s_setprio 0
	s_setprio 1
	v_mfma_f32_16x16x32_bf16 v[60:63], v[138:141], v[184:187], v[60:63]
	v_mfma_f32_16x16x32_bf16 v[56:59], v[146:149], v[184:187], v[56:59]
	v_mfma_f32_16x16x32_bf16 v[40:43], v[146:149], v[192:195], v[40:43]
	v_mfma_f32_16x16x32_bf16 v[44:47], v[138:141], v[192:195], v[44:47]
	v_mfma_f32_16x16x32_bf16 v[28:31], v[138:141], v[200:203], v[28:31]
	v_mfma_f32_16x16x32_bf16 v[24:27], v[146:149], v[200:203], v[24:27]
	v_mfma_f32_16x16x32_bf16 v[8:11], v[146:149], v[208:211], v[8:11]
	v_mfma_f32_16x16x32_bf16 v[12:15], v[138:141], v[208:211], v[12:15]
	s_setprio 0
	s_setprio 1
	v_mfma_f32_16x16x32_bf16 v[52:55], v[150:153], v[166:169], v[52:55]
	v_mfma_f32_16x16x32_bf16 v[48:51], v[158:161], v[166:169], v[48:51]
	v_mfma_f32_16x16x32_bf16 v[32:35], v[158:161], v[188:191], v[32:35]
	v_mfma_f32_16x16x32_bf16 v[36:39], v[150:153], v[188:191], v[36:39]
	v_mfma_f32_16x16x32_bf16 v[20:23], v[150:153], v[196:199], v[20:23]
	v_mfma_f32_16x16x32_bf16 v[16:19], v[158:161], v[196:199], v[16:19]
	v_mfma_f32_16x16x32_bf16 v[0:3], v[158:161], v[204:207], v[0:3]
	v_mfma_f32_16x16x32_bf16 v[4:7], v[150:153], v[204:207], v[4:7]
	s_setprio 0
	s_setprio 1
	v_mfma_f32_16x16x32_bf16 v[52:55], v[154:157], v[184:187], v[52:55]
	v_mfma_f32_16x16x32_bf16 v[48:51], v[162:165], v[184:187], v[48:51]
	v_mfma_f32_16x16x32_bf16 v[32:35], v[162:165], v[192:195], v[32:35]
	v_mfma_f32_16x16x32_bf16 v[36:39], v[154:157], v[192:195], v[36:39]
	v_mfma_f32_16x16x32_bf16 v[20:23], v[154:157], v[200:203], v[20:23]
	v_mfma_f32_16x16x32_bf16 v[16:19], v[162:165], v[200:203], v[16:19]
	v_mfma_f32_16x16x32_bf16 v[0:3], v[162:165], v[208:211], v[0:3]
	v_mfma_f32_16x16x32_bf16 v[4:7], v[154:157], v[208:211], v[4:7]
	s_setprio 0
	s_barrier
	s_add_i32 s16, 0, 0x18000
	v_add_u32_e32 v128, s16, v174
	s_add_i32 s17, 0, 0x1c000
	ds_read_b128 v[134:137], v128
	ds_read_b128 v[138:141], v128 offset:1024
	ds_read_b128 v[142:145], v180
	ds_read_b128 v[146:149], v180 offset:1024
	v_add_u32_e32 v128, s17, v174
	ds_read_b128 v[150:153], v128
	ds_read_b128 v[154:157], v128 offset:1024
	ds_read_b128 v[158:161], v181
	ds_read_b128 v[162:165], v181 offset:1024
	s_add_u32 s50, s34, 0x100000
	v_mov_b32_e32 v128, v172
	s_mov_b32 m0, s89
	ds_read_b128 v[166:169], v179 offset:32768
	ds_read_b128 v[184:187], v179 offset:33792
	ds_read_b128 v[188:191], v179 offset:34816
	ds_read_b128 v[192:195], v179 offset:35840
	ds_read_b128 v[196:199], v179 offset:36864
	ds_read_b128 v[200:203], v179 offset:37888
	ds_read_b128 v[204:207], v179 offset:38912
	ds_read_b128 v[208:211], v179 offset:39936
	s_addc_u32 s51, s35, 0
	s_nop 0
	global_load_lds_dwordx4 v128, s[50:51]
	v_mov_b32_e32 v128, v173
	s_mov_b32 m0, s90
	s_nop 0
	global_load_lds_dwordx4 v128, s[50:51]
	s_waitcnt vmcnt(8)
	s_waitcnt lgkmcnt(0)
	s_barrier
	s_setprio 1
	s_waitcnt lgkmcnt(0)
	v_mfma_f32_16x16x32_bf16 v[124:127], v[134:137], v[166:169], v[124:127]
	v_mfma_f32_16x16x32_bf16 v[120:123], v[142:145], v[166:169], v[120:123]
	v_mfma_f32_16x16x32_bf16 v[104:107], v[142:145], v[188:191], v[104:107]
	v_mfma_f32_16x16x32_bf16 v[108:111], v[134:137], v[188:191], v[108:111]
	v_mfma_f32_16x16x32_bf16 v[92:95], v[134:137], v[196:199], v[92:95]
	v_mfma_f32_16x16x32_bf16 v[88:91], v[142:145], v[196:199], v[88:91]
	v_mfma_f32_16x16x32_bf16 v[72:75], v[142:145], v[204:207], v[72:75]
	v_mfma_f32_16x16x32_bf16 v[76:79], v[134:137], v[204:207], v[76:79]
	s_setprio 0
	s_setprio 1
	v_mfma_f32_16x16x32_bf16 v[124:127], v[138:141], v[184:187], v[124:127]
	v_mfma_f32_16x16x32_bf16 v[120:123], v[146:149], v[184:187], v[120:123]
	v_mfma_f32_16x16x32_bf16 v[104:107], v[146:149], v[192:195], v[104:107]
	v_mfma_f32_16x16x32_bf16 v[108:111], v[138:141], v[192:195], v[108:111]
	v_mfma_f32_16x16x32_bf16 v[92:95], v[138:141], v[200:203], v[92:95]
	v_mfma_f32_16x16x32_bf16 v[88:91], v[146:149], v[200:203], v[88:91]
	v_mfma_f32_16x16x32_bf16 v[72:75], v[146:149], v[208:211], v[72:75]
	v_mfma_f32_16x16x32_bf16 v[76:79], v[138:141], v[208:211], v[76:79]
	s_setprio 0
	s_setprio 1
	v_mfma_f32_16x16x32_bf16 v[116:119], v[150:153], v[166:169], v[116:119]
	v_mfma_f32_16x16x32_bf16 v[112:115], v[158:161], v[166:169], v[112:115]
	v_mfma_f32_16x16x32_bf16 v[96:99], v[158:161], v[188:191], v[96:99]
	v_mfma_f32_16x16x32_bf16 v[100:103], v[150:153], v[188:191], v[100:103]
	v_mfma_f32_16x16x32_bf16 v[84:87], v[150:153], v[196:199], v[84:87]
	v_mfma_f32_16x16x32_bf16 v[80:83], v[158:161], v[196:199], v[80:83]
	v_mfma_f32_16x16x32_bf16 v[64:67], v[158:161], v[204:207], v[64:67]
	v_mfma_f32_16x16x32_bf16 v[68:71], v[150:153], v[204:207], v[68:71]
	s_setprio 0
	s_setprio 1
	v_mfma_f32_16x16x32_bf16 v[116:119], v[154:157], v[184:187], v[116:119]
	v_mfma_f32_16x16x32_bf16 v[112:115], v[162:165], v[184:187], v[112:115]
	v_mfma_f32_16x16x32_bf16 v[96:99], v[162:165], v[192:195], v[96:99]
	v_mfma_f32_16x16x32_bf16 v[100:103], v[154:157], v[192:195], v[100:103]
	v_mfma_f32_16x16x32_bf16 v[84:87], v[154:157], v[200:203], v[84:87]
	v_mfma_f32_16x16x32_bf16 v[80:83], v[162:165], v[200:203], v[80:83]
	v_mfma_f32_16x16x32_bf16 v[64:67], v[162:165], v[208:211], v[64:67]
	v_mfma_f32_16x16x32_bf16 v[68:71], v[154:157], v[208:211], v[68:71]
	s_setprio 0
	s_barrier
; #define PG8_LDA(dst, b, h) do { if constexpr (FP8) { _Pragma("unroll") for (int m = 0; m < 4; ++m) dst##8[m] = PG8_LD8(PG8_SA(b, h), aoff, aoff1, m); } \
;         else { _Pragma("unroll") for (int m = 0; m < 4; ++m) _Pragma("unroll") for (int k = 0; k < 2; ++k) dst[m][k] = *(const LAS bf16x8*)(lds + PG8_SA(b, h) + (k ? aoff1 : aoff) + m * 2048); } } while (0)
; #define PG8_LDB(dst, b, h) do { if constexpr (FP8) { dst##8[0] = PG8_LD8(PG8_SB(b, h), boff, boff1, 0); dst##8[1] = PG8_LD8(PG8_SB(b, h), boff, boff1, 1); } \
;         else { _Pragma("unroll") for (int n = 0; n < 2; ++n) _Pragma("unroll") for (int k = 0; k < 2; ++k) dst[n][k] = *(const LAS bf16x8*)(lds + PG8_SB(b, h) + (k ? boff1 : boff) + n * 2048); } } while (0)
; #define PG8_WAIT_V(n) asm volatile("s_waitcnt vmcnt(" #n ")" ::: "memory")
; #define PG8_WAIT_L(n) asm volatile("s_waitcnt lgkmcnt(" #n ")" ::: "memory")
; #define PG8_BAR __builtin_amdgcn_s_barrier()
; #define PG8_SCHED __builtin_amdgcn_sched_barrier(0)
; #define PG8_S1 PG8_STAGE(PG8_SA(1, 1), a1 + hstepA, voffA)
; #define PG8_S3 PG8_STAGE(PG8_SA(0, 1), a2 + hstepA, voffA)
; template <class Epi, class SchedT, bool ALIGN_EPI, bool SP2, bool FP8 = false>
; __device__ __forceinline__ void gemm_phase(LAS unsigned char* lds, const Gemm g, const SchedT& S, const Epi& E, const int wid) {
;     ...
;         for (int t = 0; t < nt; t += 2) {
;             const bool last = (t == nt - 2);
;             const char* a1 = cA + (size_t)(t + 1) * kstep;
;             const char* a2 = last ? nA : cA + (size_t)(t + 2) * kstep; const char* b2 = last ? nB : cB + (size_t)(t + 2) * kstep;
;             const char* a3 = a2 + kstep; const char* b3 = b2 + kstep;
;     ...
;             PG8_LDB(B0, 0, 0); PG8_LDB(B1, 0, 1); PG8_SCHED; PG8_LDA(At, 0, 0); PG8_S1;
;             PG8_WAIT_V(8); PG8_WAIT_L(0); PG8_BAR; PG8_MMAP(0, 0, 0); PG8_BAR; PG8_SCHED;
;             PG8_LDA(At, 0, 1); PG8_S2;
;             PG8_WAIT_V(8); PG8_WAIT_L(0); PG8_BAR; PG8_MMAP(1, 0, 1); PG8_BAR; PG8_SCHED;
;             PG8_LDB(B0, 1, 0); PG8_LDB(B1, 1, 1); PG8_SCHED; PG8_LDA(At, 1, 0); PG8_S3;
;             PG8_WAIT_V(8); PG8_WAIT_L(0); PG8_BAR; PG8_MMAP(0, 1, 0); PG8_BAR; PG8_SCHED;
;             PG8_LDA(At, 1, 1); PG8_S4;
;             PG8_WAIT_V(8); PG8_WAIT_L(0); PG8_BAR; PG8_MMAP(1, 1, 1); PG8_BAR; PG8_SCHED;
	v_mov_b32_e32 v128, v172
	ds_read_b128 v[166:169], v179 offset:49152
	ds_read_b128 v[184:187], v179 offset:50176
	ds_read_b128 v[188:191], v179 offset:51200
	ds_read_b128 v[192:195], v179 offset:52224
	ds_read_b128 v[196:199], v179 offset:53248
	ds_read_b128 v[200:203], v179 offset:54272
	ds_read_b128 v[204:207], v179 offset:55296
	ds_read_b128 v[208:211], v179 offset:56320
	s_add_i32 s16, s16, s86
	v_lshl_add_u64 v[170:171], s[38:39], 0, v[128:129]
	v_lshl_add_u64 v[170:171], v[170:171], 0, s[8:9]
	s_mov_b32 m0, s16
	v_mov_b32_e32 v128, v173
	global_load_lds_dwordx4 v[170:171], off
	s_add_i32 m0, s16, 0x2000
	s_nop 0
	v_lshl_add_u64 v[170:171], s[38:39], 0, v[128:129]
	s_add_u32 s38, s38, 0x100080
	v_lshl_add_u64 v[170:171], v[170:171], 0, s[8:9]
	s_addc_u32 s39, s39, 0
	v_mov_b32_e32 v128, v172
	s_add_i32 s16, s17, s86
	global_load_lds_dwordx4 v[170:171], off
	s_mov_b32 m0, s16
	s_nop 0
	global_load_lds_dwordx4 v128, s[38:39]
	v_mov_b32_e32 v128, v173
	s_add_i32 m0, s16, 0x2000
	s_nop 0
	global_load_lds_dwordx4 v128, s[38:39]
	v_mov_b32_e32 v128, v172
	s_mov_b32 m0, s92
	v_lshl_add_u64 v[170:171], s[34:35], 0, v[128:129]
	v_lshl_add_u64 v[170:171], v[170:171], 0, s[8:9]
	v_mov_b32_e32 v128, v173
	global_load_lds_dwordx4 v[170:171], off
	s_mov_b32 m0, s93
	v_lshl_add_u64 v[170:171], s[34:35], 0, v[128:129]
	v_lshl_add_u64 v[170:171], v[170:171], 0, s[8:9]
	global_load_lds_dwordx4 v[170:171], off
	s_waitcnt vmcnt(8)
	s_waitcnt lgkmcnt(0)
	s_barrier
	s_setprio 1
	s_waitcnt lgkmcnt(0)
	v_mfma_f32_16x16x32_bf16 v[60:63], v[134:137], v[166:169], v[60:63]
	v_mfma_f32_16x16x32_bf16 v[56:59], v[142:145], v[166:169], v[56:59]
	v_mfma_f32_16x16x32_bf16 v[40:43], v[142:145], v[188:191], v[40:43]
	v_mfma_f32_16x16x32_bf16 v[44:47], v[134:137], v[188:191], v[44:47]
	v_mfma_f32_16x16x32_bf16 v[28:31], v[134:137], v[196:199], v[28:31]
	v_mfma_f32_16x16x32_bf16 v[24:27], v[142:145], v[196:199], v[24:27]
	v_mfma_f32_16x16x32_bf16 v[8:11], v[142:145], v[204:207], v[8:11]
	v_mfma_f32_16x16x32_bf16 v[12:15], v[134:137], v[204:207], v[12:15]
	s_setprio 0
	s_setprio 1
	v_mfma_f32_16x16x32_bf16 v[60:63], v[138:141], v[184:187], v[60:63]
	v_mfma_f32_16x16x32_bf16 v[56:59], v[146:149], v[184:187], v[56:59]
	v_mfma_f32_16x16x32_bf16 v[40:43], v[146:149], v[192:195], v[40:43]
	v_mfma_f32_16x16x32_bf16 v[44:47], v[138:141], v[192:195], v[44:47]
	v_mfma_f32_16x16x32_bf16 v[28:31], v[138:141], v[200:203], v[28:31]
	v_mfma_f32_16x16x32_bf16 v[24:27], v[146:149], v[200:203], v[24:27]
	v_mfma_f32_16x16x32_bf16 v[8:11], v[146:149], v[208:211], v[8:11]
	v_mfma_f32_16x16x32_bf16 v[12:15], v[138:141], v[208:211], v[12:15]
	s_setprio 0
	s_setprio 1
	v_mfma_f32_16x16x32_bf16 v[52:55], v[150:153], v[166:169], v[52:55]
	v_mfma_f32_16x16x32_bf16 v[48:51], v[158:161], v[166:169], v[48:51]
	v_mfma_f32_16x16x32_bf16 v[32:35], v[158:161], v[188:191], v[32:35]
	v_mfma_f32_16x16x32_bf16 v[36:39], v[150:153], v[188:191], v[36:39]
	v_mfma_f32_16x16x32_bf16 v[20:23], v[150:153], v[196:199], v[20:23]
	v_mfma_f32_16x16x32_bf16 v[16:19], v[158:161], v[196:199], v[16:19]
	v_mfma_f32_16x16x32_bf16 v[0:3], v[158:161], v[204:207], v[0:3]
	v_mfma_f32_16x16x32_bf16 v[4:7], v[150:153], v[204:207], v[4:7]
	s_setprio 0
	s_setprio 1
	v_mfma_f32_16x16x32_bf16 v[52:55], v[154:157], v[184:187], v[52:55]
	v_mfma_f32_16x16x32_bf16 v[48:51], v[162:165], v[184:187], v[48:51]
	v_mfma_f32_16x16x32_bf16 v[32:35], v[162:165], v[192:195], v[32:35]
	v_mfma_f32_16x16x32_bf16 v[36:39], v[154:157], v[192:195], v[36:39]
	v_mfma_f32_16x16x32_bf16 v[20:23], v[154:157], v[200:203], v[20:23]
	v_mfma_f32_16x16x32_bf16 v[16:19], v[162:165], v[200:203], v[16:19]
	v_mfma_f32_16x16x32_bf16 v[0:3], v[162:165], v[208:211], v[0:3]
	v_mfma_f32_16x16x32_bf16 v[4:7], v[154:157], v[208:211], v[4:7]
	s_setprio 0
	s_barrier
	s_add_u32 s24, s24, 0x100
	s_addc_u32 s25, s25, 0
	s_add_u32 s46, s46, 0x100
	s_addc_u32 s47, s47, 0
	s_cmp_ge_i32 s48, s30
	s_mov_b32 s34, s48
	s_cbranch_scc0 .LBB0_970
	s_and_b64 vcc, exec, s[96:97]
	s_cbranch_vccz .LBB0_973
